# attention loop: bf16 rounding of P by v_cvt_pk_bf16_f32 instead of the integer bit trick (48 -> 8 VALU ops per key tile), same values
# baseline (speedup 1.0000x reference)
.LBB0_627:
	s_add_i32 s2, s39, s46
	s_addk_i32 s2, 0xff80
	s_cmp_lt_i32 s2, 0
	s_cbranch_scc1 .LBB0_626
	v_add_u32_e32 v34, s46, v89
	v_add_u32_e32 v0, 0xffffff80, v34
	v_lshlrev_b64 v[38:39], s19, v[0:1]
	v_add_u32_e32 v0, 0xffffff88, v34
	v_lshlrev_b64 v[114:115], s19, v[0:1]
	v_add_u32_e32 v0, 0xffffff90, v34
	v_lshlrev_b64 v[150:151], s19, v[0:1]
	v_add_u32_e32 v0, 0xffffff98, v34
	v_lshlrev_b64 v[152:153], s19, v[0:1]
	v_add_u32_e32 v0, s46, v131
	v_lshlrev_b64 v[34:35], s19, v[0:1]
	v_mad_u64_u32 v[40:41], s[2:3], v34, s20, v[100:101]
	v_mad_u32_u24 v41, v35, s20, v41
	global_load_dwordx4 v[34:37], v[40:41], off offset:1536
	global_load_dwordx4 v[134:137], v[40:41], off offset:1568
	global_load_dwordx4 v[138:141], v[40:41], off offset:1600
	global_load_dwordx4 v[142:145], v[40:41], off offset:1632
	v_mad_u64_u32 v[40:41], s[2:3], v38, s20, v[98:99]
	v_mad_u32_u24 v41, v39, s20, v41
	v_and_b32_e32 v38, 64, v125
	global_load_dwordx4 v[146:149], v[40:41], off offset:3072
	v_add_u32_e32 v96, 64, v38
	v_add_u32_e32 v175, v132, v67
	v_add_u32_e32 v176, v132, v66
	v_cvt_f32_i32_e32 v157, v175
	v_cvt_f32_i32_e32 v156, v176
	v_add_u32_e32 v177, v69, v132
	v_add_u32_e32 v178, v68, v132
	v_cvt_f32_i32_e32 v159, v177
	v_cvt_f32_i32_e32 v158, v178
	v_xor_b32_e32 v0, 32, v125
	v_add_u32_e32 v168, v74, v132
	v_add_u32_e32 v179, v71, v132
	v_add_u32_e32 v180, v70, v132
	v_cvt_f32_i32_e32 v91, v168
	v_cvt_f32_i32_e32 v161, v179
	v_cvt_f32_i32_e32 v160, v180
	v_cmp_lt_i32_e32 vcc, v0, v96
	v_pk_mul_f32 v[156:157], v[102:103], v[156:157]
	v_pk_mul_f32 v[158:159], v[102:103], v[158:159]
	v_cndmask_b32_e32 v0, v125, v0, vcc
	v_cmp_gt_u32_e32 vcc, s21, v175
	v_lshlrev_b32_e32 v184, 2, v0
	v_add_u32_e32 v163, v75, v132
	v_mad_u64_u32 v[166:167], s[2:3], v114, s20, v[98:99]
	v_pk_mul_f32 v[160:161], v[102:103], v[160:161]
	v_mad_u32_u24 v167, v115, s20, v167
	v_mad_u64_u32 v[114:115], s[2:3], v150, s20, v[98:99]
	v_mad_u32_u24 v115, v151, s20, v115
	v_mad_u64_u32 v[150:151], s[2:3], v152, s20, v[98:99]
	v_mov_b32_e32 v155, v97
	v_add_u32_e32 v170, v76, v132
	v_mad_u32_u24 v151, v153, s20, v151
	global_load_dwordx4 v[186:189], v[166:167], off offset:3072
	global_load_dwordx4 v[190:193], v[114:115], off offset:3072
	global_load_dwordx4 v[194:197], v[150:151], off offset:3072
	v_mov_b32_e32 v117, v97
	v_add_u32_e32 v169, v77, v132
	v_mov_b32_e32 v113, v97
	v_add_u32_e32 v172, v78, v132
	v_mov_b32_e32 v111, v97
	v_add_u32_e32 v174, v80, v132
	v_mov_b32_e32 v109, v97
	v_add_u32_e32 v171, v79, v132
	v_mov_b32_e32 v107, v97
	v_add_u32_e32 v173, v81, v132
	v_mov_b32_e32 v105, v97
	v_add_u32_e32 v182, v73, v132
	v_add_u32_e32 v183, v72, v132
	v_cvt_f32_i32_e32 v165, v182
	v_cvt_f32_i32_e32 v164, v183
	s_waitcnt vmcnt(7)
	v_mfma_f32_32x32x16_bf16 v[34:49], v[34:37], v[50:53], 0
	s_waitcnt vmcnt(6)
	v_mfma_f32_32x32x16_bf16 v[34:49], v[134:137], v[54:57], v[34:49]
	s_waitcnt vmcnt(5)
	v_mfma_f32_32x32x16_bf16 v[34:49], v[138:141], v[58:61], v[34:49]
	s_waitcnt vmcnt(3)
	ds_write_b128 v123, v[146:149]
	s_waitcnt vmcnt(2)
	ds_write_b128 v123, v[186:189] offset:1024
	s_waitcnt vmcnt(1)
	ds_write_b128 v123, v[190:193] offset:2048
	s_waitcnt vmcnt(0)
	ds_write_b128 v123, v[194:197] offset:3072
	v_mfma_f32_32x32x16_bf16 v[34:49], v[142:145], v[62:65], v[34:49]
	s_waitcnt lgkmcnt(0)
	s_nop 11
	v_mov_b32_e32 v96, v42
	v_mov_b32_e32 v116, v43
	v_mov_b32_e32 v42, v34
	v_mov_b32_e32 v43, v36
	v_pk_fma_f32 v[42:43], v[42:43], s[16:17], v[156:157] op_sel_hi:[1,0,1] neg_lo:[0,0,1] neg_hi:[0,0,1]
	v_mov_b32_e32 v36, v35
	v_cndmask_b32_e32 v0, v126, v43, vcc
	v_cmp_gt_u32_e32 vcc, s21, v176
	v_mov_b32_e32 v110, v46
	v_pk_fma_f32 v[36:37], v[36:37], s[16:17], v[158:159] op_sel_hi:[1,0,1] neg_lo:[0,0,1] neg_hi:[0,0,1]
	v_cndmask_b32_e32 v46, v126, v42, vcc
	v_cmp_gt_u32_e32 vcc, s21, v177
	v_mov_b32_e32 v108, v47
	v_mov_b32_e32 v34, v38
	v_mov_b32_e32 v35, v40
	v_mov_b32_e32 v40, v39
	v_pk_mul_f32 v[38:39], v[96:97], v[90:91]
	v_cvt_f32_i32_e32 v91, v163
	v_cndmask_b32_e32 v47, v126, v37, vcc
	v_cmp_gt_u32_e32 vcc, s21, v178
	v_mov_b32_e32 v106, v48
	v_pk_fma_f32 v[34:35], v[34:35], s[16:17], v[160:161] op_sel_hi:[1,0,1] neg_lo:[0,0,1] neg_hi:[0,0,1]
	v_cndmask_b32_e32 v48, v126, v36, vcc
	v_cmp_gt_u32_e32 vcc, s21, v179
	v_mov_b32_e32 v104, v49
	v_mov_b32_e32 v154, v44
	v_cndmask_b32_e32 v49, v126, v35, vcc
	v_cmp_gt_u32_e32 vcc, s21, v180
	v_mov_b32_e32 v112, v45
	v_mov_b32_e32 v44, v38
	v_cndmask_b32_e32 v96, v126, v34, vcc
	v_max3_f32 v34, v46, s22, v48
	v_max3_f32 v114, v34, v0, v47
	v_pk_mul_f32 v[34:35], v[154:155], v[90:91]
	v_cvt_f32_i32_e32 v91, v170
	v_mov_b32_e32 v45, v34
	v_mov_b32_e32 v34, v39
	v_pk_add_f32 v[34:35], v[44:45], v[34:35] neg_lo:[0,1] neg_hi:[0,1]
	v_pk_mul_f32 v[36:37], v[116:117], v[90:91]
	v_cvt_f32_i32_e32 v91, v169
	v_cmp_gt_u32_e32 vcc, s21, v163
	v_mov_b32_e32 v38, v36
	s_nop 0
	v_cndmask_b32_e32 v44, v126, v35, vcc
	v_cmp_gt_u32_e32 vcc, s21, v168
	s_nop 1
	v_cndmask_b32_e32 v45, v126, v34, vcc
	v_pk_mul_f32 v[34:35], v[112:113], v[90:91]
	v_cvt_f32_i32_e32 v91, v172
	v_mov_b32_e32 v39, v34
	v_mov_b32_e32 v34, v37
	v_pk_add_f32 v[34:35], v[38:39], v[34:35] neg_lo:[0,1] neg_hi:[0,1]
	v_pk_mul_f32 v[36:37], v[110:111], v[90:91]
	v_cvt_f32_i32_e32 v91, v174
	v_cmp_gt_u32_e32 vcc, s21, v169
	v_pk_mul_f32 v[38:39], v[108:109], v[90:91]
	v_cvt_f32_i32_e32 v91, v171
	v_cndmask_b32_e32 v110, v126, v35, vcc
	v_cmp_gt_u32_e32 vcc, s21, v170
	v_pk_mul_f32 v[42:43], v[106:107], v[90:91]
	v_cvt_f32_i32_e32 v91, v173
	v_cndmask_b32_e32 v108, v126, v34, vcc
	v_mov_b32_e32 v34, v36
	v_mov_b32_e32 v35, v42
	v_mov_b32_e32 v42, v37
	v_pk_add_f32 v[34:35], v[34:35], v[42:43] neg_lo:[0,1] neg_hi:[0,1]
	v_cmp_gt_u32_e32 vcc, s21, v171
	v_mov_b32_e32 v36, v38
	s_nop 0
	v_cndmask_b32_e32 v42, v126, v35, vcc
	v_cmp_gt_u32_e32 vcc, s21, v172
	s_nop 1
	v_cndmask_b32_e32 v43, v126, v34, vcc
	v_pk_mul_f32 v[34:35], v[104:105], v[90:91]
	v_cmp_gt_u32_e32 vcc, s21, v173
	v_mov_b32_e32 v37, v34
	v_mov_b32_e32 v34, v39
	v_pk_add_f32 v[34:35], v[36:37], v[34:35] neg_lo:[0,1] neg_hi:[0,1]
	s_nop 0
	v_cndmask_b32_e32 v91, v126, v35, vcc
	v_cmp_gt_u32_e32 vcc, s21, v174
	s_nop 1
	v_cndmask_b32_e32 v104, v126, v34, vcc
	v_pk_mul_f32 v[34:35], v[102:103], v[164:165]
	v_cmp_gt_u32_e32 vcc, s21, v182
	v_pk_fma_f32 v[34:35], v[40:41], s[16:17], v[34:35] op_sel_hi:[1,0,1] neg_lo:[0,0,1] neg_hi:[0,0,1]
	s_nop 0
	v_cndmask_b32_e32 v105, v126, v35, vcc
	v_cmp_gt_u32_e32 vcc, s21, v183
	s_nop 1
	v_cndmask_b32_e32 v106, v126, v34, vcc
	v_max3_f32 v34, v114, v96, v106
	v_max3_f32 v34, v34, v49, v105
	v_max3_f32 v34, v34, v45, v108
	v_max3_f32 v34, v34, v44, v110
	v_max3_f32 v34, v34, v43, v104
	v_max3_f32 v34, v34, v42, v91
	ds_bpermute_b32 v35, v184, v34
	s_waitcnt lgkmcnt(0)
	v_max3_f32 v107, v133, v34, v35
	v_sub_f32_e32 v34, v46, v107
	v_sub_f32_e32 v111, v133, v107
	v_mov_b32_e32 v133, v107
	v_exp_f32_e32 v109, v34
	ds_read_b64_tr_b16 v[38:39], v124
	ds_read_b64_tr_b16 v[40:41], v124 offset:1024
	ds_read_b64_tr_b16 v[36:37], v124 offset:1088
	ds_read_b64_tr_b16 v[34:35], v124 offset:64
	v_sub_f32_e32 v112, v48, v107
	s_nop 1
	v_sub_f32_e32 v113, v0, v107
	v_exp_f32_e32 v112, v112
	s_nop 0
	v_exp_f32_e32 v113, v113
	v_cmp_lt_f32_e32 vcc, s23, v0
	v_sub_f32_e32 v0, v47, v107
	v_cmp_lt_f32_e64 s[2:3], s23, v46
	v_cndmask_b32_e32 v113, 0, v113, vcc
	s_nop 0
	v_cndmask_b32_e64 v46, 0, v109, s[2:3]
	s_nop 0
	v_exp_f32_e32 v0, v0
	v_cmp_lt_f32_e32 vcc, s23, v47
	s_nop 0
	s_nop 0
	v_cndmask_b32_e32 v47, 0, v0, vcc
	v_cmp_lt_f32_e32 vcc, s23, v48
	v_sub_f32_e32 v0, v96, v107
	s_nop 0
	v_cndmask_b32_e32 v48, 0, v112, vcc
	s_nop 1
	v_sub_f32_e32 v109, v49, v107
	v_exp_f32_e32 v0, v0
	s_nop 0
	v_exp_f32_e32 v109, v109
	v_cmp_lt_f32_e32 vcc, s23, v49
	s_nop 1
	v_cndmask_b32_e32 v49, 0, v109, vcc
	v_cmp_lt_f32_e32 vcc, s23, v96
	s_nop 1
	v_cndmask_b32_e32 v96, 0, v0, vcc
	v_sub_f32_e32 v0, v106, v107
	s_nop 1
	v_sub_f32_e32 v109, v105, v107
	v_exp_f32_e32 v0, v0
	s_nop 0
	v_exp_f32_e32 v109, v109
	v_cmp_lt_f32_e32 vcc, s23, v105
	s_nop 1
	v_cndmask_b32_e32 v105, 0, v109, vcc
	v_cmp_lt_f32_e32 vcc, s23, v106
	s_nop 1
	v_cndmask_b32_e32 v106, 0, v0, vcc
	v_sub_f32_e32 v0, v45, v107
	s_nop 1
	v_sub_f32_e32 v109, v44, v107
	v_exp_f32_e32 v0, v0
	s_nop 0
	v_exp_f32_e32 v109, v109
	v_cmp_lt_f32_e32 vcc, s23, v44
	s_nop 1
	v_cndmask_b32_e32 v109, 0, v109, vcc
	v_cmp_lt_f32_e32 vcc, s23, v45
	s_nop 1
	v_cndmask_b32_e32 v112, 0, v0, vcc
	v_sub_f32_e32 v0, v108, v107
	s_nop 1
	v_sub_f32_e32 v44, v110, v107
	v_exp_f32_e32 v0, v0
	s_nop 0
	v_exp_f32_e32 v44, v44
	v_cmp_lt_f32_e32 vcc, s23, v110
	s_nop 1
	v_cndmask_b32_e32 v110, 0, v44, vcc
	v_cmp_lt_f32_e32 vcc, s23, v108
	s_nop 1
	v_cndmask_b32_e32 v108, 0, v0, vcc
	v_sub_f32_e32 v0, v43, v107
	s_nop 1
	v_sub_f32_e32 v44, v42, v107
	v_exp_f32_e32 v0, v0
	s_nop 0
	v_exp_f32_e32 v44, v44
	v_cmp_lt_f32_e32 vcc, s23, v42
	s_nop 0
	s_nop 0
	v_cndmask_b32_e32 v114, 0, v44, vcc
	v_cmp_lt_f32_e32 vcc, s23, v43
	s_nop 0
	s_nop 0
	v_cndmask_b32_e32 v115, 0, v0, vcc
	v_sub_f32_e32 v0, v104, v107
	s_nop 1
	v_sub_f32_e32 v42, v91, v107
	v_exp_f32_e32 v0, v0
	s_nop 0
	v_exp_f32_e32 v42, v42
	v_cmp_lt_f32_e32 vcc, s23, v91
	s_nop 1
	v_cndmask_b32_e32 v91, 0, v42, vcc
	v_cmp_lt_f32_e32 vcc, s23, v104
	s_nop 1
	v_cndmask_b32_e32 v104, 0, v0, vcc
	v_add_f32_e32 v0, v46, v48
	v_add_f32_e32 v0, v113, v0
	v_add_f32_e32 v0, v47, v0
	v_add_f32_e32 v0, v96, v0
	v_add_f32_e32 v0, v106, v0
	v_add_f32_e32 v0, v49, v0
	v_add_f32_e32 v0, v105, v0
	v_add_f32_e32 v0, v112, v0
	v_add_f32_e32 v0, v108, v0
	v_add_f32_e32 v0, v109, v0
	v_mov_b32_e32 v42, v111
	v_add_f32_e32 v0, v110, v0
	v_exp_f32_e32 v42, v42
	v_add_f32_e32 v0, v115, v0
	v_add_f32_e32 v0, v104, v0
	v_add_f32_e32 v111, v114, v0
	v_mov_b32_e32 v0, v42
	v_pk_mul_f32 v[32:33], v[32:33], v[0:1] op_sel_hi:[1,0]
	v_pk_mul_f32 v[30:31], v[30:31], v[0:1] op_sel_hi:[1,0]
	v_pk_mul_f32 v[28:29], v[28:29], v[0:1] op_sel_hi:[1,0]
	v_pk_mul_f32 v[26:27], v[26:27], v[0:1] op_sel_hi:[1,0]
	v_pk_mul_f32 v[24:25], v[24:25], v[0:1] op_sel_hi:[1,0]
	v_pk_mul_f32 v[22:23], v[22:23], v[0:1] op_sel_hi:[1,0]
	v_pk_mul_f32 v[20:21], v[20:21], v[0:1] op_sel_hi:[1,0]
	v_pk_mul_f32 v[18:19], v[18:19], v[0:1] op_sel_hi:[1,0]
	v_pk_mul_f32 v[16:17], v[16:17], v[0:1] op_sel_hi:[1,0]
	v_cvt_pk_bf16_f32 v45, v49, v105
	v_cvt_pk_bf16_f32 v44, v96, v106
	v_cvt_pk_bf16_f32 v43, v113, v47
	v_cvt_pk_bf16_f32 v42, v46, v48
	v_pk_mul_f32 v[14:15], v[14:15], v[0:1] op_sel_hi:[1,0]
	v_pk_mul_f32 v[12:13], v[12:13], v[0:1] op_sel_hi:[1,0]
	v_pk_mul_f32 v[10:11], v[10:11], v[0:1] op_sel_hi:[1,0]
	v_pk_mul_f32 v[8:9], v[8:9], v[0:1] op_sel_hi:[1,0]
	v_pk_mul_f32 v[6:7], v[6:7], v[0:1] op_sel_hi:[1,0]
	v_pk_mul_f32 v[4:5], v[4:5], v[0:1] op_sel_hi:[1,0]
	v_pk_mul_f32 v[2:3], v[2:3], v[0:1] op_sel_hi:[1,0]
	s_waitcnt lgkmcnt(2)
	v_mfma_f32_32x32x16_bf16 v[18:33], v[38:41], v[42:45], v[18:33]
	s_waitcnt lgkmcnt(0)
	v_mfma_f32_32x32x16_bf16 v[2:17], v[34:37], v[42:45], v[2:17]
	ds_read_b64_tr_b16 v[34:35], v124 offset:2048
	ds_read_b64_tr_b16 v[36:37], v124 offset:3072
	v_cvt_pk_bf16_f32 v41, v114, v91
	v_cvt_pk_bf16_f32 v40, v115, v104
	v_cvt_pk_bf16_f32 v39, v109, v110
	v_cvt_pk_bf16_f32 v38, v112, v108
	ds_read_b64_tr_b16 v[44:45], v124 offset:3136
	ds_read_b64_tr_b16 v[42:43], v124 offset:2112
	s_waitcnt lgkmcnt(2)
	v_mfma_f32_32x32x16_bf16 v[18:33], v[34:37], v[38:41], v[18:33]
	v_add_f32_e32 v34, v91, v111
	ds_bpermute_b32 v35, v184, v34
	s_waitcnt lgkmcnt(0)
	s_waitcnt lgkmcnt(0)
	v_add_f32_e32 v34, v34, v35
	v_mfma_f32_32x32x16_bf16 v[2:17], v[42:45], v[38:41], v[2:17]
	v_fmac_f32_e32 v34, v130, v0
	v_mov_b32_e32 v130, v34
	s_branch .LBB0_626
